# v60 + w1 epilogue output stores issued as buffer_store_dwordx4 (SRD + 32-bit offsets) instead of flat-global 64-bit-address stores
# speedup vs baseline: 1.0031x; 1.0031x over previous
; #define PG8_STAGE(bufoff, gbase, voff) do { _Pragma("unroll") for (int _i = 0; _i < 2; ++_i) \
;         __builtin_amdgcn_global_load_lds((const unsigned*)((const char*)(gbase) + (voff)[_i]), (LAS unsigned*)(lds + (bufoff) + ldsw + _i * 8192), 16, 0, 0); } while (0)
; #define PG8_LDA(dst, b, h) do { _Pragma("unroll") for (int m = 0; m < 4; ++m) _Pragma("unroll") for (int k = 0; k < 2; ++k) dst[m][k] = *(const LAS bf16x8*)(lds + PG8_SA(b, h) + aoff + m * 2048 + k * 1024); } while (0)
; #define PG8_LDB(dst, b, h) do { _Pragma("unroll") for (int n = 0; n < 2; ++n) _Pragma("unroll") for (int k = 0; k < 2; ++k) dst[n][k] = *(const LAS bf16x8*)(lds + PG8_SB(b, h) + boff + n * 2048 + k * 1024); } while (0)
; #define PG8_MMA(ai, bj, At, Bt) do { __builtin_amdgcn_s_setprio(1); _Pragma("unroll") for (int m = 0; m < 4; ++m) _Pragma("unroll") for (int n = 0; n < 2; ++n) _Pragma("unroll") for (int k = 0; k < 2; ++k) \
;         acc[ai][bj][m][n] = __builtin_amdgcn_mfma_f32_16x16x32_bf16(Bt[n][k], At[m][k], acc[ai][bj][m][n], 0, 0, 0); __builtin_amdgcn_s_setprio(0); } while (0)
; #define PG8_WAIT_V(n) asm volatile("s_waitcnt vmcnt(" #n ")" ::: "memory")
; #define PG8_WAIT_L(n) asm volatile("s_waitcnt lgkmcnt(" #n ")" ::: "memory")
; #define PG8_BAR __builtin_amdgcn_s_barrier()
; #define PG8_SCHED __builtin_amdgcn_sched_barrier(0)
; template <class Epi, class Sched>
; __device__ __forceinline__ void gemm_phase(LAS unsigned char* lds, const Gemm g, const Sched& S, const Epi& E) {
;     ...
;             PG8_LDB(B0, 0, 0); PG8_SCHED; PG8_LDA(At, 0, 0); PG8_STAGE(PG8_SA(1, 1), a1 + hstep, voffA);
;             PG8_WAIT_L(8); PG8_BAR; PG8_WAIT_L(0); PG8_MMA(0, 0, At, B0); PG8_BAR; PG8_SCHED;
;             PG8_LDB(B1, 0, 1); PG8_STAGE(PG8_SB(0, 0), b2, voffB);
;             PG8_BAR; PG8_WAIT_L(0); PG8_MMA(0, 1, At, B1); PG8_BAR;
;             PG8_LDA(At, 0, 1); PG8_STAGE(PG8_SA(0, 0), a2, voffA);
;             PG8_BAR; PG8_WAIT_L(0); PG8_MMA(1, 0, At, B0); PG8_BAR; PG8_SCHED;
;             PG8_STAGE(PG8_SB(0, 1), b2 + hstep, voffB);
;             PG8_WAIT_V(6); PG8_BAR; PG8_MMA(1, 1, At, B1); PG8_BAR;
;             PG8_LDB(B0, 1, 0); PG8_SCHED; PG8_LDA(At, 1, 0); PG8_STAGE(PG8_SA(0, 1), a2 + hstep, voffA);
;             PG8_WAIT_L(8); PG8_BAR; PG8_WAIT_L(0); PG8_MMA(0, 0, At, B0); PG8_BAR; PG8_SCHED;
.LBB0_73:
	s_add_u32 s38, s46, 0xfff80080
	s_addc_u32 s39, s47, -1
	s_cmp_eq_u32 s73, 28
	s_cselect_b32 s51, s29, s39
	s_cselect_b32 s50, s69, s38
	s_cselect_b32 s49, s27, s72
	s_cselect_b32 s48, s70, s71
	s_add_i32 m0, s9, 0xc000
	s_nop 0
	global_load_lds_dwordx4 v138, s[46:47]
	s_add_i32 m0, s9, 0xe000
	s_nop 0
	global_load_lds_dwordx4 v136, s[46:47]
	s_add_i32 s74, 0, 0x10000
	v_add_u32_e32 v140, s74, v143
	ds_read_b128 v[146:149], v140
	ds_read_b128 v[150:153], v140 offset:1024
	ds_read_b128 v[154:157], v140 offset:2048
	ds_read_b128 v[160:163], v140 offset:3072
	ds_read_b128 v[164:167], v145
	ds_read_b128 v[168:171], v145 offset:1024
	ds_read_b128 v[172:175], v145 offset:2048
	ds_read_b128 v[176:179], v145 offset:3072
	ds_read_b128 v[180:183], v145 offset:4096
	ds_read_b128 v[184:187], v145 offset:5120
	ds_read_b128 v[188:191], v145 offset:6144
	ds_read_b128 v[192:195], v145 offset:7168
	s_add_i32 s75, 0, 0x14000
	v_add_u32_e32 v140, s75, v143
	ds_read_b128 v[196:199], v140
	ds_read_b128 v[200:203], v140 offset:1024
	ds_read_b128 v[204:207], v140 offset:2048
	ds_read_b128 v[210:213], v140 offset:3072
	s_waitcnt lgkmcnt(4)
	s_barrier
	s_waitcnt lgkmcnt(0)
	v_mfma_f32_16x16x32_bf16 v[126:129], v[146:149], v[164:167], v[126:129]
	v_mfma_f32_16x16x32_bf16 v[122:125], v[154:157], v[164:167], v[122:125]
	v_mfma_f32_16x16x32_bf16 v[110:113], v[146:149], v[172:175], v[110:113]
	v_mfma_f32_16x16x32_bf16 v[106:109], v[154:157], v[172:175], v[106:109]
	v_mfma_f32_16x16x32_bf16 v[94:97], v[146:149], v[180:183], v[94:97]
	v_mfma_f32_16x16x32_bf16 v[90:93], v[154:157], v[180:183], v[90:93]
	v_mfma_f32_16x16x32_bf16 v[78:81], v[146:149], v[188:191], v[78:81]
	v_mfma_f32_16x16x32_bf16 v[74:77], v[154:157], v[188:191], v[74:77]
	v_mfma_f32_16x16x32_bf16 v[126:129], v[150:153], v[168:171], v[126:129]
	v_mfma_f32_16x16x32_bf16 v[122:125], v[160:163], v[168:171], v[122:125]
	v_mfma_f32_16x16x32_bf16 v[110:113], v[150:153], v[176:179], v[110:113]
	v_mfma_f32_16x16x32_bf16 v[106:109], v[160:163], v[176:179], v[106:109]
	v_mfma_f32_16x16x32_bf16 v[94:97], v[150:153], v[184:187], v[94:97]
	v_mfma_f32_16x16x32_bf16 v[90:93], v[160:163], v[184:187], v[90:93]
	v_mfma_f32_16x16x32_bf16 v[78:81], v[150:153], v[192:195], v[78:81]
	v_mfma_f32_16x16x32_bf16 v[74:77], v[160:163], v[192:195], v[74:77]
	v_mfma_f32_16x16x32_bf16 v[118:121], v[196:199], v[164:167], v[118:121]
	v_mfma_f32_16x16x32_bf16 v[114:117], v[204:207], v[164:167], v[114:117]
	v_mfma_f32_16x16x32_bf16 v[102:105], v[196:199], v[172:175], v[102:105]
	v_mfma_f32_16x16x32_bf16 v[98:101], v[204:207], v[172:175], v[98:101]
	v_mfma_f32_16x16x32_bf16 v[86:89], v[196:199], v[180:183], v[86:89]
	v_mfma_f32_16x16x32_bf16 v[82:85], v[204:207], v[180:183], v[82:85]
	v_mfma_f32_16x16x32_bf16 v[70:73], v[196:199], v[188:191], v[70:73]
	v_mfma_f32_16x16x32_bf16 v[66:69], v[204:207], v[188:191], v[66:69]
	v_mfma_f32_16x16x32_bf16 v[118:121], v[200:203], v[168:171], v[118:121]
	v_mfma_f32_16x16x32_bf16 v[114:117], v[210:213], v[168:171], v[114:117]
	v_mfma_f32_16x16x32_bf16 v[102:105], v[200:203], v[176:179], v[102:105]
	v_mfma_f32_16x16x32_bf16 v[98:101], v[210:213], v[176:179], v[98:101]
	v_mfma_f32_16x16x32_bf16 v[86:89], v[200:203], v[184:187], v[86:89]
	v_mfma_f32_16x16x32_bf16 v[82:85], v[210:213], v[184:187], v[82:85]
	v_mfma_f32_16x16x32_bf16 v[70:73], v[200:203], v[192:195], v[70:73]
	v_mfma_f32_16x16x32_bf16 v[66:69], v[210:213], v[192:195], v[66:69]
	s_barrier
	s_add_i32 s38, s74, s56
	s_mov_b32 m0, s38
	s_nop 0
	global_load_lds_dwordx4 v0, s[48:49]
	s_add_i32 m0, s38, 0x2000
	s_nop 0
	global_load_lds_dwordx4 v130, s[48:49]
	s_mov_b32 m0, s9
	s_nop 0
	global_load_lds_dwordx4 v134, s[50:51]
	s_mov_b32 m0, s60
	s_nop 0
	global_load_lds_dwordx4 v132, s[50:51]
	ds_read_b128 v[164:167], v145 offset:16384
	ds_read_b128 v[168:171], v145 offset:17408
	ds_read_b128 v[172:175], v145 offset:18432
	ds_read_b128 v[176:179], v145 offset:19456
	ds_read_b128 v[180:183], v145 offset:20480
	ds_read_b128 v[184:187], v145 offset:21504
	ds_read_b128 v[188:191], v145 offset:22528
	ds_read_b128 v[192:195], v145 offset:23552
	s_waitcnt vmcnt(4)
	s_waitcnt lgkmcnt(0)
	s_barrier
	v_mfma_f32_16x16x32_bf16 v[62:65], v[146:149], v[164:167], v[62:65]
	v_mfma_f32_16x16x32_bf16 v[58:61], v[154:157], v[164:167], v[58:61]
	v_mfma_f32_16x16x32_bf16 v[46:49], v[146:149], v[172:175], v[46:49]
	v_mfma_f32_16x16x32_bf16 v[42:45], v[154:157], v[172:175], v[42:45]
	v_mfma_f32_16x16x32_bf16 v[30:33], v[146:149], v[180:183], v[30:33]
	v_mfma_f32_16x16x32_bf16 v[26:29], v[154:157], v[180:183], v[26:29]
	v_mfma_f32_16x16x32_bf16 v[14:17], v[146:149], v[188:191], v[14:17]
	v_mfma_f32_16x16x32_bf16 v[10:13], v[154:157], v[188:191], v[10:13]
	v_mfma_f32_16x16x32_bf16 v[62:65], v[150:153], v[168:171], v[62:65]
	v_mfma_f32_16x16x32_bf16 v[58:61], v[160:163], v[168:171], v[58:61]
	v_mfma_f32_16x16x32_bf16 v[46:49], v[150:153], v[176:179], v[46:49]
	v_mfma_f32_16x16x32_bf16 v[42:45], v[160:163], v[176:179], v[42:45]
	v_mfma_f32_16x16x32_bf16 v[30:33], v[150:153], v[184:187], v[30:33]
	v_mfma_f32_16x16x32_bf16 v[26:29], v[160:163], v[184:187], v[26:29]
	v_mfma_f32_16x16x32_bf16 v[14:17], v[150:153], v[192:195], v[14:17]
	v_mfma_f32_16x16x32_bf16 v[10:13], v[160:163], v[192:195], v[10:13]
	v_mfma_f32_16x16x32_bf16 v[54:57], v[196:199], v[164:167], v[54:57]
	v_mfma_f32_16x16x32_bf16 v[50:53], v[204:207], v[164:167], v[50:53]
	v_mfma_f32_16x16x32_bf16 v[38:41], v[196:199], v[172:175], v[38:41]
	v_mfma_f32_16x16x32_bf16 v[34:37], v[204:207], v[172:175], v[34:37]
	v_mfma_f32_16x16x32_bf16 v[22:25], v[196:199], v[180:183], v[22:25]
	v_mfma_f32_16x16x32_bf16 v[18:21], v[204:207], v[180:183], v[18:21]
	v_mfma_f32_16x16x32_bf16 v[6:9], v[196:199], v[188:191], v[6:9]
	v_mfma_f32_16x16x32_bf16 v[2:5], v[204:207], v[188:191], v[2:5]
	v_mfma_f32_16x16x32_bf16 v[54:57], v[200:203], v[168:171], v[54:57]
	v_mfma_f32_16x16x32_bf16 v[50:53], v[210:213], v[168:171], v[50:53]
	v_mfma_f32_16x16x32_bf16 v[38:41], v[200:203], v[176:179], v[38:41]
	v_mfma_f32_16x16x32_bf16 v[34:37], v[210:213], v[176:179], v[34:37]
	v_mfma_f32_16x16x32_bf16 v[22:25], v[200:203], v[184:187], v[22:25]
	v_mfma_f32_16x16x32_bf16 v[18:21], v[210:213], v[184:187], v[18:21]
	v_mfma_f32_16x16x32_bf16 v[6:9], v[200:203], v[192:195], v[6:9]
	v_mfma_f32_16x16x32_bf16 v[2:5], v[210:213], v[192:195], v[2:5]
	s_barrier
; #define PG8_STAGE(bufoff, gbase, voff) do { _Pragma("unroll") for (int _i = 0; _i < 2; ++_i) \
;         __builtin_amdgcn_global_load_lds((const unsigned*)((const char*)(gbase) + (voff)[_i]), (LAS unsigned*)(lds + (bufoff) + ldsw + _i * 8192), 16, 0, 0); } while (0)
; #define PG8_LDA(dst, b, h) do { _Pragma("unroll") for (int m = 0; m < 4; ++m) _Pragma("unroll") for (int k = 0; k < 2; ++k) dst[m][k] = *(const LAS bf16x8*)(lds + PG8_SA(b, h) + aoff + m * 2048 + k * 1024); } while (0)
; #define PG8_LDB(dst, b, h) do { _Pragma("unroll") for (int n = 0; n < 2; ++n) _Pragma("unroll") for (int k = 0; k < 2; ++k) dst[n][k] = *(const LAS bf16x8*)(lds + PG8_SB(b, h) + boff + n * 2048 + k * 1024); } while (0)
; #define PG8_MMA(ai, bj, At, Bt) do { __builtin_amdgcn_s_setprio(1); _Pragma("unroll") for (int m = 0; m < 4; ++m) _Pragma("unroll") for (int n = 0; n < 2; ++n) _Pragma("unroll") for (int k = 0; k < 2; ++k) \
;         acc[ai][bj][m][n] = __builtin_amdgcn_mfma_f32_16x16x32_bf16(Bt[n][k], At[m][k], acc[ai][bj][m][n], 0, 0, 0); __builtin_amdgcn_s_setprio(0); } while (0)
; #define PG8_WAIT_V(n) asm volatile("s_waitcnt vmcnt(" #n ")" ::: "memory")
; #define PG8_WAIT_L(n) asm volatile("s_waitcnt lgkmcnt(" #n ")" ::: "memory")
; #define PG8_BAR __builtin_amdgcn_s_barrier()
; #define PG8_SCHED __builtin_amdgcn_sched_barrier(0)
; template <class Epi, class Sched>
; __device__ __forceinline__ void gemm_phase(LAS unsigned char* lds, const Gemm g, const Sched& S, const Epi& E) {
;     ...
;             PG8_WAIT_L(8); PG8_BAR; PG8_WAIT_L(0); PG8_MMA(0, 0, At, B0); PG8_BAR; PG8_SCHED;
;             PG8_LDB(B1, 1, 1); PG8_STAGE(PG8_SB(1, 0), b3, voffB);
;             PG8_BAR; PG8_WAIT_L(0); PG8_MMA(0, 1, At, B1); PG8_BAR;
;             PG8_LDA(At, 1, 1); PG8_STAGE(PG8_SA(1, 0), a3, voffA);
;             PG8_BAR; PG8_WAIT_L(0); PG8_MMA(1, 0, At, B0); PG8_BAR; PG8_SCHED;
;             PG8_STAGE(PG8_SB(1, 1), b3 + hstep, voffB);
;             PG8_WAIT_V(6); PG8_BAR; PG8_MMA(1, 1, At, B1); PG8_BAR;
	s_add_u32 s38, s48, 0x80000
	s_addc_u32 s39, s49, 0
	s_add_i32 s74, s75, s56
	s_mov_b32 m0, s74
	s_nop 0
	global_load_lds_dwordx4 v0, s[38:39]
	s_add_i32 m0, s74, 0x2000
	s_nop 0
	global_load_lds_dwordx4 v130, s[38:39]
	s_add_u32 s38, s50, 0x80000
	s_addc_u32 s39, s51, 0
	s_mov_b32 m0, s61
	s_nop 0
	global_load_lds_dwordx4 v134, s[38:39]
	s_mov_b32 m0, s62
	s_nop 0
	global_load_lds_dwordx4 v132, s[38:39]
	s_add_i32 s74, 0, 0x18000
	v_add_u32_e32 v160, s74, v143
	ds_read_b128 v[146:149], v160
	ds_read_b128 v[150:153], v160 offset:1024
	ds_read_b128 v[154:157], v160 offset:2048
	ds_read_b128 v[160:163], v160 offset:3072
	ds_read_b128 v[164:167], v145 offset:32768
	ds_read_b128 v[168:171], v145 offset:33792
	ds_read_b128 v[172:175], v145 offset:34816
	ds_read_b128 v[176:179], v145 offset:35840
	ds_read_b128 v[180:183], v145 offset:36864
	ds_read_b128 v[184:187], v145 offset:37888
	ds_read_b128 v[188:191], v145 offset:38912
	ds_read_b128 v[192:195], v145 offset:39936
	s_nop 0
	v_add_u32_e32 v210, 0x1c000, v143
	ds_read_b128 v[196:199], v210
	ds_read_b128 v[200:203], v210 offset:1024
	ds_read_b128 v[204:207], v210 offset:2048
	ds_read_b128 v[210:213], v210 offset:3072
	s_waitcnt lgkmcnt(4)
	s_barrier
	s_waitcnt lgkmcnt(0)
	v_mfma_f32_16x16x32_bf16 v[126:129], v[146:149], v[164:167], v[126:129]
	v_mfma_f32_16x16x32_bf16 v[122:125], v[154:157], v[164:167], v[122:125]
	v_mfma_f32_16x16x32_bf16 v[110:113], v[146:149], v[172:175], v[110:113]
	v_mfma_f32_16x16x32_bf16 v[106:109], v[154:157], v[172:175], v[106:109]
	v_mfma_f32_16x16x32_bf16 v[94:97], v[146:149], v[180:183], v[94:97]
	v_mfma_f32_16x16x32_bf16 v[90:93], v[154:157], v[180:183], v[90:93]
	v_mfma_f32_16x16x32_bf16 v[78:81], v[146:149], v[188:191], v[78:81]
	v_mfma_f32_16x16x32_bf16 v[74:77], v[154:157], v[188:191], v[74:77]
	v_mfma_f32_16x16x32_bf16 v[126:129], v[150:153], v[168:171], v[126:129]
	v_mfma_f32_16x16x32_bf16 v[122:125], v[160:163], v[168:171], v[122:125]
	v_mfma_f32_16x16x32_bf16 v[110:113], v[150:153], v[176:179], v[110:113]
	v_mfma_f32_16x16x32_bf16 v[106:109], v[160:163], v[176:179], v[106:109]
	v_mfma_f32_16x16x32_bf16 v[94:97], v[150:153], v[184:187], v[94:97]
	v_mfma_f32_16x16x32_bf16 v[90:93], v[160:163], v[184:187], v[90:93]
	v_mfma_f32_16x16x32_bf16 v[78:81], v[150:153], v[192:195], v[78:81]
	v_mfma_f32_16x16x32_bf16 v[74:77], v[160:163], v[192:195], v[74:77]
	v_mfma_f32_16x16x32_bf16 v[118:121], v[196:199], v[164:167], v[118:121]
	v_mfma_f32_16x16x32_bf16 v[114:117], v[204:207], v[164:167], v[114:117]
	v_mfma_f32_16x16x32_bf16 v[102:105], v[196:199], v[172:175], v[102:105]
	v_mfma_f32_16x16x32_bf16 v[98:101], v[204:207], v[172:175], v[98:101]
	v_mfma_f32_16x16x32_bf16 v[86:89], v[196:199], v[180:183], v[86:89]
	v_mfma_f32_16x16x32_bf16 v[82:85], v[204:207], v[180:183], v[82:85]
	v_mfma_f32_16x16x32_bf16 v[70:73], v[196:199], v[188:191], v[70:73]
	v_mfma_f32_16x16x32_bf16 v[66:69], v[204:207], v[188:191], v[66:69]
	v_mfma_f32_16x16x32_bf16 v[118:121], v[200:203], v[168:171], v[118:121]
	v_mfma_f32_16x16x32_bf16 v[114:117], v[210:213], v[168:171], v[114:117]
	v_mfma_f32_16x16x32_bf16 v[102:105], v[200:203], v[176:179], v[102:105]
	v_mfma_f32_16x16x32_bf16 v[98:101], v[210:213], v[176:179], v[98:101]
	v_mfma_f32_16x16x32_bf16 v[86:89], v[200:203], v[184:187], v[86:89]
	v_mfma_f32_16x16x32_bf16 v[82:85], v[210:213], v[184:187], v[82:85]
	v_mfma_f32_16x16x32_bf16 v[70:73], v[200:203], v[192:195], v[70:73]
	v_mfma_f32_16x16x32_bf16 v[66:69], v[210:213], v[192:195], v[66:69]
	s_barrier
	s_add_i32 s38, s74, s56
	s_add_u32 s100, s48, s36
	s_addc_u32 s101, s49, s37
	s_mov_b32 m0, s38
	s_nop 0
	global_load_lds_dwordx4 v0, s[100:101]
	s_add_i32 m0, s38, 0x2000
	s_nop 0
	global_load_lds_dwordx4 v130, s[100:101]
	s_mov_b32 m0, s64
	s_add_u32 s100, s50, s36
	s_addc_u32 s101, s51, s37
	global_load_lds_dwordx4 v134, s[100:101]
	s_mov_b32 m0, s65
	s_nop 0
	global_load_lds_dwordx4 v132, s[100:101]
	ds_read_b128 v[164:167], v145 offset:49152
	ds_read_b128 v[168:171], v145 offset:50176
	ds_read_b128 v[172:175], v145 offset:51200
	ds_read_b128 v[176:179], v145 offset:52224
	ds_read_b128 v[180:183], v145 offset:53248
	ds_read_b128 v[184:187], v145 offset:54272
	ds_read_b128 v[188:191], v145 offset:55296
	ds_read_b128 v[192:195], v145 offset:56320
	s_waitcnt vmcnt(4)
	s_waitcnt lgkmcnt(0)
	s_barrier
	v_mfma_f32_16x16x32_bf16 v[62:65], v[146:149], v[164:167], v[62:65]
	v_mfma_f32_16x16x32_bf16 v[58:61], v[154:157], v[164:167], v[58:61]
	v_mfma_f32_16x16x32_bf16 v[46:49], v[146:149], v[172:175], v[46:49]
	v_mfma_f32_16x16x32_bf16 v[42:45], v[154:157], v[172:175], v[42:45]
	v_mfma_f32_16x16x32_bf16 v[30:33], v[146:149], v[180:183], v[30:33]
	v_mfma_f32_16x16x32_bf16 v[26:29], v[154:157], v[180:183], v[26:29]
	v_mfma_f32_16x16x32_bf16 v[14:17], v[146:149], v[188:191], v[14:17]
	v_mfma_f32_16x16x32_bf16 v[10:13], v[154:157], v[188:191], v[10:13]
	v_mfma_f32_16x16x32_bf16 v[62:65], v[150:153], v[168:171], v[62:65]
	v_mfma_f32_16x16x32_bf16 v[58:61], v[160:163], v[168:171], v[58:61]
	v_mfma_f32_16x16x32_bf16 v[46:49], v[150:153], v[176:179], v[46:49]
	v_mfma_f32_16x16x32_bf16 v[42:45], v[160:163], v[176:179], v[42:45]
	v_mfma_f32_16x16x32_bf16 v[30:33], v[150:153], v[184:187], v[30:33]
	v_mfma_f32_16x16x32_bf16 v[26:29], v[160:163], v[184:187], v[26:29]
	v_mfma_f32_16x16x32_bf16 v[14:17], v[150:153], v[192:195], v[14:17]
	v_mfma_f32_16x16x32_bf16 v[10:13], v[160:163], v[192:195], v[10:13]
	s_add_u32 s38, s48, 0x80080
	s_addc_u32 s39, s49, 0
	s_add_i32 s48, s56, 0x1c000
	s_mov_b32 m0, s48
	s_nop 0
	global_load_lds_dwordx4 v0, s[38:39]
	s_add_i32 m0, s48, 0x2000
	s_nop 0
	global_load_lds_dwordx4 v130, s[38:39]
	v_mfma_f32_16x16x32_bf16 v[54:57], v[196:199], v[164:167], v[54:57]
	v_mfma_f32_16x16x32_bf16 v[50:53], v[204:207], v[164:167], v[50:53]
	v_mfma_f32_16x16x32_bf16 v[38:41], v[196:199], v[172:175], v[38:41]
	v_mfma_f32_16x16x32_bf16 v[34:37], v[204:207], v[172:175], v[34:37]
	v_mfma_f32_16x16x32_bf16 v[22:25], v[196:199], v[180:183], v[22:25]
	v_mfma_f32_16x16x32_bf16 v[18:21], v[204:207], v[180:183], v[18:21]
	v_mfma_f32_16x16x32_bf16 v[6:9], v[196:199], v[188:191], v[6:9]
	v_mfma_f32_16x16x32_bf16 v[2:5], v[204:207], v[188:191], v[2:5]
	v_mfma_f32_16x16x32_bf16 v[54:57], v[200:203], v[168:171], v[54:57]
	v_mfma_f32_16x16x32_bf16 v[50:53], v[210:213], v[168:171], v[50:53]
	v_mfma_f32_16x16x32_bf16 v[38:41], v[200:203], v[176:179], v[38:41]
	v_mfma_f32_16x16x32_bf16 v[34:37], v[210:213], v[176:179], v[34:37]
	v_mfma_f32_16x16x32_bf16 v[22:25], v[200:203], v[184:187], v[22:25]
	v_mfma_f32_16x16x32_bf16 v[18:21], v[210:213], v[184:187], v[18:21]
	v_mfma_f32_16x16x32_bf16 v[6:9], v[200:203], v[192:195], v[6:9]
	v_mfma_f32_16x16x32_bf16 v[2:5], v[210:213], v[192:195], v[2:5]
	s_add_i32 s73, s73, 2
	s_add_u32 s71, s71, 0x100
	s_addc_u32 s72, s72, 0
	s_add_u32 s46, s46, 0x100
	s_addc_u32 s47, s47, 0
	s_cmp_gt_u32 s73, 29
	s_barrier
; __device__ __forceinline__ unsigned cvt_pk_bf16(float lo, float hi) { unsigned r; asm("v_cvt_pk_bf16_f32 %0, %1, %2" : "=v"(r) : "v"(lo), "v"(hi)); return r; }
;     __device__ __forceinline__ void operator()(const f32x4 (&acc)[2][2][4][2], const Unit& u, int wr, int wc, int fr, int fq) const {
;     ...
;             for (int m = 0; m < 4; ++m) { bf16_t* rowp = O + (size_t)(row0 + ai * HALF + m * 16) * ldc + col0;
; #pragma unroll
;                 for (int bj = 0; bj < 2; ++bj) { f32x4 v0 = acc[ai][bj][m][0], v1 = acc[ai][bj][m][1];
;                     if (ACT == 1) {
; #pragma unroll
;                         for (int j = 0; j < 4; ++j) { float a = fmaxf(v0[j], 0.f), b = fmaxf(v1[j], 0.f); v0[j] = a * a; v1[j] = b * b; } }
;                     u32x4 w; w.x = cvt_pk_bf16(v0[0], v0[1]); w.y = cvt_pk_bf16(v0[2], v0[3]); w.z = cvt_pk_bf16(v1[0], v1[1]); w.w = cvt_pk_bf16(v1[2], v1[3]);
;                     if (ACT == 1) __builtin_nontemporal_store(w, (u32x4*)(rowp + bj * HALF));
;                     else *(u32x4*)(rowp + bj * HALF) = w; } }
	s_cbranch_scc0 .LBB0_73
	s_mov_b32 s72, s24
	s_and_b32 s73, s25, 0xffff
	s_mov_b32 s74, 0x20000000
	s_mov_b32 s75, 0x20000
	v_lshl_add_u32 v146, s8, 8, v142
	v_max_f32_e32 v122, v122, v122
	v_ashrrev_i32_e32 v147, 31, v146
	v_max_f32_e32 v122, 0, v122
	v_max_f32_e32 v123, v123, v123
	v_max_f32_e32 v124, v124, v124
	v_lshl_or_b32 v140, s68, 8, v144
	v_lshlrev_b64 v[148:149], 14, v[146:147]
	v_mul_f32_e32 v147, v122, v122
	v_max_f32_e32 v122, v127, v127
	v_max_f32_e32 v123, 0, v123
	v_max_f32_e32 v124, 0, v124
	v_ashrrev_i32_e32 v141, 31, v140
	v_max_f32_e32 v126, v126, v126
	v_max_f32_e32 v122, 0, v122
	v_mul_f32_e32 v127, v123, v123
	v_max_f32_e32 v123, v128, v128
	v_mul_f32_e32 v128, v124, v124
	v_max_f32_e32 v124, v129, v129
	v_max_f32_e32 v125, v125, v125
	v_lshl_add_u64 v[148:149], s[24:25], 0, v[148:149]
	v_lshlrev_b64 v[150:151], 1, v[140:141]
	v_max_f32_e32 v126, 0, v126
	v_mul_f32_e32 v122, v122, v122
	v_max_f32_e32 v123, 0, v123
	v_max_f32_e32 v124, 0, v124
	v_max_f32_e32 v125, 0, v125
	v_max_f32_e32 v114, v114, v114
	v_lshl_add_u64 v[140:141], v[148:149], 0, v[150:151]
	v_mul_f32_e32 v126, v126, v126
	v_mul_f32_e32 v123, v123, v123
	v_mul_f32_e32 v124, v124, v124
	v_mul_f32_e32 v125, v125, v125
	v_cvt_pk_bf16_f32 v122, v126, v122
	v_max_f32_e32 v114, 0, v114
	v_max_f32_e32 v115, v115, v115
	v_max_f32_e32 v116, v116, v116
	v_cvt_pk_bf16_f32 v123, v123, v124
	v_cvt_pk_bf16_f32 v124, v147, v127
	v_cvt_pk_bf16_f32 v125, v128, v125
	v_subrev_u32_e32 v226, s24, v140
	buffer_store_dwordx4 v[122:125], v226, s[72:75], 0 offen nt
	v_max_f32_e32 v115, 0, v115
	v_max_f32_e32 v116, 0, v116
	v_mul_f32_e32 v122, v114, v114
	v_max_f32_e32 v114, v119, v119
	v_max_f32_e32 v118, v118, v118
	v_max_f32_e32 v114, 0, v114
	v_mul_f32_e32 v119, v115, v115
	v_max_f32_e32 v115, v120, v120
	v_mul_f32_e32 v120, v116, v116
	v_max_f32_e32 v116, v121, v121
	v_max_f32_e32 v117, v117, v117
	v_max_f32_e32 v118, 0, v118
	v_mul_f32_e32 v114, v114, v114
	v_max_f32_e32 v115, 0, v115
	v_max_f32_e32 v116, 0, v116
	v_max_f32_e32 v117, 0, v117
	v_mul_f32_e32 v118, v118, v118
	v_mul_f32_e32 v115, v115, v115
	v_mul_f32_e32 v116, v116, v116
	v_mul_f32_e32 v117, v117, v117
	v_cvt_pk_bf16_f32 v114, v118, v114
	v_max_f32_e32 v106, v106, v106
	v_cvt_pk_bf16_f32 v115, v115, v116
	v_cvt_pk_bf16_f32 v116, v122, v119
	v_cvt_pk_bf16_f32 v117, v120, v117
	v_subrev_u32_e32 v226, s24, v140
	buffer_store_dwordx4 v[114:117], v226, s[72:75], 0 offen offset:256 nt
	v_max_f32_e32 v106, 0, v106
	v_max_f32_e32 v107, v107, v107
	v_or_b32_e32 v114, 16, v146
	v_max_f32_e32 v108, v108, v108
	v_ashrrev_i32_e32 v115, 31, v114
	v_mul_f32_e32 v116, v106, v106
	v_max_f32_e32 v106, v111, v111
	v_max_f32_e32 v107, 0, v107
	v_max_f32_e32 v108, 0, v108
	v_lshlrev_b64 v[114:115], 14, v[114:115]
	v_max_f32_e32 v110, v110, v110
	v_max_f32_e32 v106, 0, v106
	v_mul_f32_e32 v111, v107, v107
	v_max_f32_e32 v107, v112, v112
	v_mul_f32_e32 v112, v108, v108
	v_max_f32_e32 v108, v113, v113
	v_max_f32_e32 v109, v109, v109
	v_lshl_add_u64 v[114:115], s[24:25], 0, v[114:115]
	v_max_f32_e32 v110, 0, v110
	v_mul_f32_e32 v106, v106, v106
	v_max_f32_e32 v107, 0, v107
	v_max_f32_e32 v108, 0, v108
	v_max_f32_e32 v109, 0, v109
	v_max_f32_e32 v98, v98, v98
	v_lshl_add_u64 v[114:115], v[114:115], 0, v[150:151]
	v_mul_f32_e32 v110, v110, v110
	v_mul_f32_e32 v107, v107, v107
	v_mul_f32_e32 v108, v108, v108
	v_mul_f32_e32 v109, v109, v109
	v_cvt_pk_bf16_f32 v106, v110, v106
	v_max_f32_e32 v98, 0, v98
	v_max_f32_e32 v99, v99, v99
	v_max_f32_e32 v100, v100, v100
	v_cvt_pk_bf16_f32 v107, v107, v108
	v_cvt_pk_bf16_f32 v108, v116, v111
	v_cvt_pk_bf16_f32 v109, v112, v109
	v_subrev_u32_e32 v226, s24, v114
	buffer_store_dwordx4 v[106:109], v226, s[72:75], 0 offen nt
	v_max_f32_e32 v99, 0, v99
	v_max_f32_e32 v100, 0, v100
	v_mul_f32_e32 v106, v98, v98
	v_max_f32_e32 v98, v103, v103
	v_max_f32_e32 v102, v102, v102
	v_max_f32_e32 v98, 0, v98
	v_mul_f32_e32 v103, v99, v99
	v_max_f32_e32 v99, v104, v104
	v_mul_f32_e32 v104, v100, v100
	v_max_f32_e32 v100, v105, v105
	v_max_f32_e32 v101, v101, v101
	v_max_f32_e32 v102, 0, v102
	v_mul_f32_e32 v98, v98, v98
	v_max_f32_e32 v99, 0, v99
	v_max_f32_e32 v100, 0, v100
	v_max_f32_e32 v101, 0, v101
	v_mul_f32_e32 v102, v102, v102
	v_mul_f32_e32 v99, v99, v99
	v_mul_f32_e32 v100, v100, v100
	v_mul_f32_e32 v101, v101, v101
	v_cvt_pk_bf16_f32 v98, v102, v98
	v_max_f32_e32 v90, v90, v90
	v_cvt_pk_bf16_f32 v99, v99, v100
	v_cvt_pk_bf16_f32 v100, v106, v103
	v_cvt_pk_bf16_f32 v101, v104, v101
	v_subrev_u32_e32 v226, s24, v114
	buffer_store_dwordx4 v[98:101], v226, s[72:75], 0 offen offset:256 nt
	v_max_f32_e32 v90, 0, v90
	v_max_f32_e32 v91, v91, v91
	v_or_b32_e32 v98, 32, v146
	v_max_f32_e32 v92, v92, v92
	v_ashrrev_i32_e32 v99, 31, v98
	v_mul_f32_e32 v100, v90, v90
	v_max_f32_e32 v90, v95, v95
	v_max_f32_e32 v91, 0, v91
	v_max_f32_e32 v92, 0, v92
	v_lshlrev_b64 v[98:99], 14, v[98:99]
	v_max_f32_e32 v94, v94, v94
	v_max_f32_e32 v90, 0, v90
	v_mul_f32_e32 v95, v91, v91
	v_max_f32_e32 v91, v96, v96
	v_mul_f32_e32 v96, v92, v92
	v_max_f32_e32 v92, v97, v97
	v_max_f32_e32 v93, v93, v93
	v_lshl_add_u64 v[98:99], s[24:25], 0, v[98:99]
	v_max_f32_e32 v94, 0, v94
	v_mul_f32_e32 v90, v90, v90
	v_max_f32_e32 v91, 0, v91
	v_max_f32_e32 v92, 0, v92
	v_max_f32_e32 v93, 0, v93
	v_max_f32_e32 v82, v82, v82
	v_lshl_add_u64 v[98:99], v[98:99], 0, v[150:151]
	v_mul_f32_e32 v94, v94, v94
	v_mul_f32_e32 v91, v91, v91
	v_mul_f32_e32 v92, v92, v92
	v_mul_f32_e32 v93, v93, v93
	v_cvt_pk_bf16_f32 v90, v94, v90
	v_max_f32_e32 v82, 0, v82
	v_max_f32_e32 v83, v83, v83
	v_max_f32_e32 v84, v84, v84
	v_cvt_pk_bf16_f32 v91, v91, v92
; __device__ __forceinline__ unsigned cvt_pk_bf16(float lo, float hi) { unsigned r; asm("v_cvt_pk_bf16_f32 %0, %1, %2" : "=v"(r) : "v"(lo), "v"(hi)); return r; }
;     __device__ __forceinline__ void operator()(const f32x4 (&acc)[2][2][4][2], const Unit& u, int wr, int wc, int fr, int fq) const {
;     ...
;             for (int m = 0; m < 4; ++m) { bf16_t* rowp = O + (size_t)(row0 + ai * HALF + m * 16) * ldc + col0;
; #pragma unroll
;                 for (int bj = 0; bj < 2; ++bj) { f32x4 v0 = acc[ai][bj][m][0], v1 = acc[ai][bj][m][1];
;                     if (ACT == 1) {
; #pragma unroll
;                         for (int j = 0; j < 4; ++j) { float a = fmaxf(v0[j], 0.f), b = fmaxf(v1[j], 0.f); v0[j] = a * a; v1[j] = b * b; } }
;                     u32x4 w; w.x = cvt_pk_bf16(v0[0], v0[1]); w.y = cvt_pk_bf16(v0[2], v0[3]); w.z = cvt_pk_bf16(v1[0], v1[1]); w.w = cvt_pk_bf16(v1[2], v1[3]);
;                     if (ACT == 1) __builtin_nontemporal_store(w, (u32x4*)(rowp + bj * HALF));
;                     else *(u32x4*)(rowp + bj * HALF) = w; } }
	v_cvt_pk_bf16_f32 v92, v100, v95
	v_cvt_pk_bf16_f32 v93, v96, v93
	v_subrev_u32_e32 v226, s24, v98
	buffer_store_dwordx4 v[90:93], v226, s[72:75], 0 offen nt
	v_max_f32_e32 v83, 0, v83
	v_max_f32_e32 v84, 0, v84
	v_mul_f32_e32 v90, v82, v82
	v_max_f32_e32 v82, v87, v87
	v_max_f32_e32 v86, v86, v86
	v_max_f32_e32 v82, 0, v82
	v_mul_f32_e32 v87, v83, v83
	v_max_f32_e32 v83, v88, v88
	v_mul_f32_e32 v88, v84, v84
	v_max_f32_e32 v84, v89, v89
	v_max_f32_e32 v85, v85, v85
	v_max_f32_e32 v86, 0, v86
	v_mul_f32_e32 v82, v82, v82
	v_max_f32_e32 v83, 0, v83
	v_max_f32_e32 v84, 0, v84
	v_max_f32_e32 v85, 0, v85
	v_mul_f32_e32 v86, v86, v86
	v_mul_f32_e32 v83, v83, v83
	v_mul_f32_e32 v84, v84, v84
	v_mul_f32_e32 v85, v85, v85
	v_cvt_pk_bf16_f32 v82, v86, v82
	v_max_f32_e32 v74, v74, v74
	v_cvt_pk_bf16_f32 v83, v83, v84
	v_cvt_pk_bf16_f32 v84, v90, v87
	v_cvt_pk_bf16_f32 v85, v88, v85
	v_subrev_u32_e32 v226, s24, v98
	buffer_store_dwordx4 v[82:85], v226, s[72:75], 0 offen offset:256 nt
	v_max_f32_e32 v74, 0, v74
	v_max_f32_e32 v75, v75, v75
	v_or_b32_e32 v82, 48, v146
	v_max_f32_e32 v76, v76, v76
	v_ashrrev_i32_e32 v83, 31, v82
	v_mul_f32_e32 v84, v74, v74
	v_max_f32_e32 v74, v79, v79
	v_max_f32_e32 v75, 0, v75
	v_max_f32_e32 v76, 0, v76
	v_lshlrev_b64 v[82:83], 14, v[82:83]
	v_max_f32_e32 v78, v78, v78
	v_max_f32_e32 v74, 0, v74
	v_mul_f32_e32 v79, v75, v75
	v_max_f32_e32 v75, v80, v80
	v_mul_f32_e32 v80, v76, v76
	v_max_f32_e32 v76, v81, v81
	v_max_f32_e32 v77, v77, v77
	v_lshl_add_u64 v[82:83], s[24:25], 0, v[82:83]
	v_max_f32_e32 v78, 0, v78
	v_mul_f32_e32 v74, v74, v74
	v_max_f32_e32 v75, 0, v75
	v_max_f32_e32 v76, 0, v76
	v_max_f32_e32 v77, 0, v77
	v_max_f32_e32 v66, v66, v66
	v_max_f32_e32 v67, v67, v67
	v_max_f32_e32 v68, v68, v68
	v_lshl_add_u64 v[82:83], v[82:83], 0, v[150:151]
	v_mul_f32_e32 v78, v78, v78
	v_mul_f32_e32 v75, v75, v75
	v_mul_f32_e32 v76, v76, v76
	v_mul_f32_e32 v77, v77, v77
	v_cvt_pk_bf16_f32 v74, v78, v74
	v_max_f32_e32 v66, 0, v66
	v_max_f32_e32 v67, 0, v67
	v_max_f32_e32 v68, 0, v68
	v_cvt_pk_bf16_f32 v75, v75, v76
	v_cvt_pk_bf16_f32 v76, v84, v79
	v_cvt_pk_bf16_f32 v77, v80, v77
	v_subrev_u32_e32 v226, s24, v82
	buffer_store_dwordx4 v[74:77], v226, s[72:75], 0 offen nt
	v_max_f32_e32 v69, v69, v69
	v_max_f32_e32 v70, v70, v70
	v_mul_f32_e32 v74, v66, v66
	v_max_f32_e32 v66, v71, v71
	v_mul_f32_e32 v71, v67, v67
	v_max_f32_e32 v67, v72, v72
	v_mul_f32_e32 v72, v68, v68
	v_max_f32_e32 v68, v73, v73
	v_max_f32_e32 v67, 0, v67
	v_max_f32_e32 v68, 0, v68
	v_max_f32_e32 v66, 0, v66
	v_mul_f32_e32 v67, v67, v67
	v_max_f32_e32 v69, 0, v69
	v_mul_f32_e32 v68, v68, v68
	v_max_f32_e32 v58, v58, v58
	v_max_f32_e32 v70, 0, v70
	v_mul_f32_e32 v66, v66, v66
	v_mul_f32_e32 v69, v69, v69
	v_cvt_pk_bf16_f32 v67, v67, v68
	v_cvt_pk_bf16_f32 v68, v74, v71
	v_max_f32_e32 v58, 0, v58
	v_max_f32_e32 v59, v59, v59
	v_max_f32_e32 v60, v60, v60
	v_mul_f32_e32 v70, v70, v70
	v_cvt_pk_bf16_f32 v66, v70, v66
	v_cvt_pk_bf16_f32 v69, v72, v69
	v_subrev_u32_e32 v226, s24, v82
	buffer_store_dwordx4 v[66:69], v226, s[72:75], 0 offen offset:256 nt
	v_max_f32_e32 v62, v62, v62
	v_max_f32_e32 v59, 0, v59
	v_mul_f32_e32 v68, v58, v58
	v_max_f32_e32 v58, v63, v63
	v_max_f32_e32 v60, 0, v60
	v_max_f32_e32 v62, 0, v62
	v_max_f32_e32 v58, 0, v58
	v_mul_f32_e32 v63, v59, v59
	v_max_f32_e32 v59, v64, v64
	v_mul_f32_e32 v64, v60, v60
	v_max_f32_e32 v60, v65, v65
	v_mul_f32_e32 v62, v62, v62
	v_mul_f32_e32 v58, v58, v58
	v_max_f32_e32 v59, 0, v59
	v_max_f32_e32 v60, 0, v60
	v_max_f32_e32 v61, v61, v61
	s_mov_b32 s8, 0x200000
	v_mul_f32_e32 v59, v59, v59
	v_max_f32_e32 v61, 0, v61
	v_mul_f32_e32 v60, v60, v60
	v_cvt_pk_bf16_f32 v58, v62, v58
	v_add_co_u32_e32 v62, vcc, s8, v140
	v_max_f32_e32 v50, v50, v50
	v_max_f32_e32 v51, v51, v51
	v_max_f32_e32 v52, v52, v52
	v_mul_f32_e32 v61, v61, v61
	v_cvt_pk_bf16_f32 v59, v59, v60
	v_cvt_pk_bf16_f32 v60, v68, v63
	v_addc_co_u32_e32 v63, vcc, 0, v141, vcc
	v_max_f32_e32 v50, 0, v50
	v_max_f32_e32 v51, 0, v51
	v_max_f32_e32 v52, 0, v52
	v_cvt_pk_bf16_f32 v61, v64, v61
	v_subrev_u32_e32 v226, s24, v62
	buffer_store_dwordx4 v[58:61], v226, s[72:75], 0 offen nt
	v_max_f32_e32 v53, v53, v53
	s_mov_b64 s[38:39], 0x200000
	v_mul_f32_e32 v58, v50, v50
	v_max_f32_e32 v50, v55, v55
	v_mul_f32_e32 v55, v51, v51
	v_max_f32_e32 v51, v56, v56
	v_mul_f32_e32 v56, v52, v52
	v_max_f32_e32 v52, v57, v57
	v_max_f32_e32 v51, 0, v51
	v_max_f32_e32 v52, 0, v52
	v_max_f32_e32 v54, v54, v54
	v_max_f32_e32 v50, 0, v50
	v_mul_f32_e32 v51, v51, v51
	v_max_f32_e32 v53, 0, v53
	v_mul_f32_e32 v52, v52, v52
	v_max_f32_e32 v42, v42, v42
	v_lshl_add_u64 v[66:67], v[140:141], 0, s[38:39]
	v_max_f32_e32 v54, 0, v54
	v_mul_f32_e32 v50, v50, v50
	v_mul_f32_e32 v53, v53, v53
	v_cvt_pk_bf16_f32 v51, v51, v52
	v_cvt_pk_bf16_f32 v52, v58, v55
	v_max_f32_e32 v42, 0, v42
	v_max_f32_e32 v43, v43, v43
	v_max_f32_e32 v44, v44, v44
	v_mul_f32_e32 v54, v54, v54
	v_cvt_pk_bf16_f32 v50, v54, v50
	v_cvt_pk_bf16_f32 v53, v56, v53
	v_subrev_u32_e32 v226, s24, v66
	buffer_store_dwordx4 v[50:53], v226, s[72:75], 0 offen offset:256 nt
	v_max_f32_e32 v46, v46, v46
	v_max_f32_e32 v43, 0, v43
	v_mul_f32_e32 v52, v42, v42
	v_max_f32_e32 v42, v47, v47
	v_max_f32_e32 v44, 0, v44
	v_max_f32_e32 v46, 0, v46
	v_max_f32_e32 v42, 0, v42
	v_mul_f32_e32 v47, v43, v43
	v_max_f32_e32 v43, v48, v48
	v_mul_f32_e32 v48, v44, v44
	v_max_f32_e32 v44, v49, v49
	v_mul_f32_e32 v46, v46, v46
	v_mul_f32_e32 v42, v42, v42
	v_max_f32_e32 v43, 0, v43
	v_max_f32_e32 v44, 0, v44
	v_max_f32_e32 v45, v45, v45
	s_mov_b32 s8, 0x240000
; __device__ __forceinline__ unsigned cvt_pk_bf16(float lo, float hi) { unsigned r; asm("v_cvt_pk_bf16_f32 %0, %1, %2" : "=v"(r) : "v"(lo), "v"(hi)); return r; }
; #define PG8_WAIT_V(n) asm volatile("s_waitcnt vmcnt(" #n ")" ::: "memory")
; #define PG8_BAR __builtin_amdgcn_s_barrier()
;     __device__ __forceinline__ void operator()(const f32x4 (&acc)[2][2][4][2], const Unit& u, int wr, int wc, int fr, int fq) const {
;     ...
;             for (int m = 0; m < 4; ++m) { bf16_t* rowp = O + (size_t)(row0 + ai * HALF + m * 16) * ldc + col0;
; #pragma unroll
;                 for (int bj = 0; bj < 2; ++bj) { f32x4 v0 = acc[ai][bj][m][0], v1 = acc[ai][bj][m][1];
;                     if (ACT == 1) {
; #pragma unroll
;                         for (int j = 0; j < 4; ++j) { float a = fmaxf(v0[j], 0.f), b = fmaxf(v1[j], 0.f); v0[j] = a * a; v1[j] = b * b; } }
;                     u32x4 w; w.x = cvt_pk_bf16(v0[0], v0[1]); w.y = cvt_pk_bf16(v0[2], v0[3]); w.z = cvt_pk_bf16(v1[0], v1[1]); w.w = cvt_pk_bf16(v1[2], v1[3]);
;                     if (ACT == 1) __builtin_nontemporal_store(w, (u32x4*)(rowp + bj * HALF));
;                     else *(u32x4*)(rowp + bj * HALF) = w; } }
; template <class Epi, class Sched>
; __device__ __forceinline__ void gemm_phase(LAS unsigned char* lds, const Gemm g, const Sched& S, const Epi& E) {
;     ...
;         if (!has_next) break;
; #pragma unroll
;         for (int a = 0; a < 2; ++a)
; #pragma unroll
;             for (int b = 0; b < 2; ++b)
; #pragma unroll
;                 for (int m = 0; m < 4; ++m)
; #pragma unroll
;                     for (int n = 0; n < 2; ++n) acc[a][b][m][n] = (f32x4){0.f, 0.f, 0.f, 0.f};
;         cur = nxt; cA = nA; cB = nB; ++ui;
;     }
;     PG8_WAIT_V(0);
;     if (wr == 0) PG8_BAR;
;     PG8_BAR;
	v_mul_f32_e32 v43, v43, v43
	v_max_f32_e32 v45, 0, v45
	v_mul_f32_e32 v44, v44, v44
	v_cvt_pk_bf16_f32 v42, v46, v42
	v_add_co_u32_e32 v46, vcc, s8, v140
	v_max_f32_e32 v34, v34, v34
	v_max_f32_e32 v35, v35, v35
	v_max_f32_e32 v36, v36, v36
	v_mul_f32_e32 v45, v45, v45
	v_cvt_pk_bf16_f32 v43, v43, v44
	v_cvt_pk_bf16_f32 v44, v52, v47
	v_addc_co_u32_e32 v47, vcc, 0, v141, vcc
	v_max_f32_e32 v34, 0, v34
	v_max_f32_e32 v35, 0, v35
	v_max_f32_e32 v36, 0, v36
	v_cvt_pk_bf16_f32 v45, v48, v45
	v_subrev_u32_e32 v226, s24, v46
	buffer_store_dwordx4 v[42:45], v226, s[72:75], 0 offen nt
	v_max_f32_e32 v37, v37, v37
	s_mov_b64 s[38:39], 0x240000
	v_mul_f32_e32 v42, v34, v34
	v_max_f32_e32 v34, v39, v39
	v_mul_f32_e32 v39, v35, v35
	v_max_f32_e32 v35, v40, v40
	v_mul_f32_e32 v40, v36, v36
	v_max_f32_e32 v36, v41, v41
	v_max_f32_e32 v35, 0, v35
	v_max_f32_e32 v36, 0, v36
	v_max_f32_e32 v38, v38, v38
	v_max_f32_e32 v34, 0, v34
	v_mul_f32_e32 v35, v35, v35
	v_max_f32_e32 v37, 0, v37
	v_mul_f32_e32 v36, v36, v36
	v_max_f32_e32 v26, v26, v26
	v_lshl_add_u64 v[50:51], v[140:141], 0, s[38:39]
	v_max_f32_e32 v38, 0, v38
	v_mul_f32_e32 v34, v34, v34
	v_mul_f32_e32 v37, v37, v37
	v_cvt_pk_bf16_f32 v35, v35, v36
	v_cvt_pk_bf16_f32 v36, v42, v39
	v_max_f32_e32 v26, 0, v26
	v_max_f32_e32 v27, v27, v27
	v_max_f32_e32 v28, v28, v28
	v_mul_f32_e32 v38, v38, v38
	v_cvt_pk_bf16_f32 v34, v38, v34
	v_cvt_pk_bf16_f32 v37, v40, v37
	v_subrev_u32_e32 v226, s24, v50
	buffer_store_dwordx4 v[34:37], v226, s[72:75], 0 offen offset:256 nt
	v_max_f32_e32 v30, v30, v30
	v_max_f32_e32 v27, 0, v27
	v_mul_f32_e32 v36, v26, v26
	v_max_f32_e32 v26, v31, v31
	v_max_f32_e32 v28, 0, v28
	v_max_f32_e32 v30, 0, v30
	v_max_f32_e32 v26, 0, v26
	v_mul_f32_e32 v31, v27, v27
	v_max_f32_e32 v27, v32, v32
	v_mul_f32_e32 v32, v28, v28
	v_max_f32_e32 v28, v33, v33
	v_mul_f32_e32 v30, v30, v30
	v_mul_f32_e32 v26, v26, v26
	v_max_f32_e32 v27, 0, v27
	v_max_f32_e32 v28, 0, v28
	v_max_f32_e32 v29, v29, v29
	s_mov_b32 s8, 0x280000
	v_mul_f32_e32 v27, v27, v27
	v_max_f32_e32 v29, 0, v29
	v_mul_f32_e32 v28, v28, v28
	v_cvt_pk_bf16_f32 v26, v30, v26
	v_add_co_u32_e32 v30, vcc, s8, v140
	v_max_f32_e32 v18, v18, v18
	v_max_f32_e32 v19, v19, v19
	v_max_f32_e32 v20, v20, v20
	v_mul_f32_e32 v29, v29, v29
	v_cvt_pk_bf16_f32 v27, v27, v28
	v_cvt_pk_bf16_f32 v28, v36, v31
	v_addc_co_u32_e32 v31, vcc, 0, v141, vcc
	v_max_f32_e32 v18, 0, v18
	v_max_f32_e32 v19, 0, v19
	v_max_f32_e32 v20, 0, v20
	v_cvt_pk_bf16_f32 v29, v32, v29
	v_subrev_u32_e32 v226, s24, v30
	buffer_store_dwordx4 v[26:29], v226, s[72:75], 0 offen nt
	v_max_f32_e32 v21, v21, v21
	s_mov_b64 s[38:39], 0x280000
	v_mul_f32_e32 v26, v18, v18
	v_max_f32_e32 v18, v23, v23
	v_mul_f32_e32 v23, v19, v19
	v_max_f32_e32 v19, v24, v24
	v_mul_f32_e32 v24, v20, v20
	v_max_f32_e32 v20, v25, v25
	v_max_f32_e32 v19, 0, v19
	v_max_f32_e32 v20, 0, v20
	v_max_f32_e32 v22, v22, v22
	v_max_f32_e32 v18, 0, v18
	v_mul_f32_e32 v19, v19, v19
	v_max_f32_e32 v21, 0, v21
	v_mul_f32_e32 v20, v20, v20
	v_max_f32_e32 v10, v10, v10
	v_lshl_add_u64 v[34:35], v[140:141], 0, s[38:39]
	v_max_f32_e32 v22, 0, v22
	v_mul_f32_e32 v18, v18, v18
	v_mul_f32_e32 v21, v21, v21
	v_cvt_pk_bf16_f32 v19, v19, v20
	v_cvt_pk_bf16_f32 v20, v26, v23
	v_max_f32_e32 v10, 0, v10
	v_max_f32_e32 v11, v11, v11
	v_max_f32_e32 v12, v12, v12
	v_mul_f32_e32 v22, v22, v22
	v_cvt_pk_bf16_f32 v18, v22, v18
	v_cvt_pk_bf16_f32 v21, v24, v21
	v_subrev_u32_e32 v226, s24, v34
	buffer_store_dwordx4 v[18:21], v226, s[72:75], 0 offen offset:256 nt
	v_max_f32_e32 v14, v14, v14
	v_max_f32_e32 v11, 0, v11
	v_mul_f32_e32 v20, v10, v10
	v_max_f32_e32 v10, v15, v15
	v_max_f32_e32 v12, 0, v12
	v_max_f32_e32 v14, 0, v14
	v_max_f32_e32 v10, 0, v10
	v_mul_f32_e32 v15, v11, v11
	v_max_f32_e32 v11, v16, v16
	v_mul_f32_e32 v16, v12, v12
	v_max_f32_e32 v12, v17, v17
	v_mul_f32_e32 v14, v14, v14
	v_mul_f32_e32 v10, v10, v10
	v_max_f32_e32 v11, 0, v11
	v_max_f32_e32 v12, 0, v12
	v_max_f32_e32 v13, v13, v13
	s_mov_b32 s8, 0x2c0000
	v_mul_f32_e32 v11, v11, v11
	v_max_f32_e32 v13, 0, v13
	v_mul_f32_e32 v12, v12, v12
	v_cvt_pk_bf16_f32 v10, v14, v10
	v_add_co_u32_e32 v14, vcc, s8, v140
	v_max_f32_e32 v2, v2, v2
	v_max_f32_e32 v3, v3, v3
	v_max_f32_e32 v4, v4, v4
	v_mul_f32_e32 v13, v13, v13
	v_cvt_pk_bf16_f32 v11, v11, v12
	v_cvt_pk_bf16_f32 v12, v20, v15
	v_addc_co_u32_e32 v15, vcc, 0, v141, vcc
	v_max_f32_e32 v2, 0, v2
	v_max_f32_e32 v3, 0, v3
	v_max_f32_e32 v4, 0, v4
	v_cvt_pk_bf16_f32 v13, v16, v13
	v_subrev_u32_e32 v226, s24, v14
	buffer_store_dwordx4 v[10:13], v226, s[72:75], 0 offen nt
	v_max_f32_e32 v5, v5, v5
	s_mov_b64 s[38:39], 0x2c0000
	v_mul_f32_e32 v10, v2, v2
	v_max_f32_e32 v2, v7, v7
	v_mul_f32_e32 v7, v3, v3
	v_max_f32_e32 v3, v8, v8
	v_mul_f32_e32 v8, v4, v4
	v_max_f32_e32 v4, v9, v9
	v_max_f32_e32 v6, v6, v6
	v_max_f32_e32 v2, 0, v2
	v_max_f32_e32 v3, 0, v3
	v_max_f32_e32 v4, 0, v4
	v_max_f32_e32 v5, 0, v5
	v_lshl_add_u64 v[18:19], v[140:141], 0, s[38:39]
	v_max_f32_e32 v6, 0, v6
	v_mul_f32_e32 v2, v2, v2
	v_mul_f32_e32 v3, v3, v3
	v_mul_f32_e32 v4, v4, v4
	v_mul_f32_e32 v5, v5, v5
	s_and_b64 vcc, exec, s[40:41]
	s_mov_b32 s68, s26
	s_mov_b32 s8, s28
	s_mov_b64 s[46:47], s[44:45]
	s_mov_b64 s[48:49], s[42:43]
	v_mul_f32_e32 v6, v6, v6
	v_cvt_pk_bf16_f32 v2, v6, v2
	v_cvt_pk_bf16_f32 v3, v3, v4
	v_cvt_pk_bf16_f32 v4, v10, v7
	v_cvt_pk_bf16_f32 v5, v8, v5
	v_subrev_u32_e32 v226, s24, v18
	buffer_store_dwordx4 v[2:5], v226, s[72:75], 0 offen offset:256 nt
	s_cbranch_vccz .LBB0_70
	s_waitcnt vmcnt(0)
	s_cmpk_gt_u32 s52, 0xff
	s_cbranch_scc1 .LBB0_77
	s_barrier
